# v1 plus padding: attention steady-loop head at 32 mod 64, later phases as v1 mod 64
# baseline (speedup 1.0000x reference)
; #define WAIT_BAR(N) asm volatile("s_waitcnt vmcnt(" #N ") lgkmcnt(0)\n\ts_barrier":::"memory")
;   #define DMA_K(t,slot) glds16(ksrc+(long)(t)*KVBLK*DM,(unsigned)__builtin_amdgcn_readfirstlane(kdst+(slot)))
;   #define DMA_V(t,slot) do{ glds16(vsrc+(long)(t)*KVBLK*DM,(unsigned)__builtin_amdgcn_readfirstlane(vdst+(slot))); glds16(vsrc+64+(long)(t)*KVBLK*DM,(unsigned)__builtin_amdgcn_readfirstlane(vdst2+(slot))); }while(0)
;   #define CMASK(P0,P1,t) do{int jb_=(t)-(NT-4); if(jb_>=0)cmask(P0,P1,jb_,qrel,hi);}while(0)
;   #define START(P0,P1) do{ resc=false; \
;     { _Pragma("unroll") for(int r=0;r<16;++r){P0[r]=fsub_s(P0[r],mhat);P1[r]=fsub_s(P1[r],mhat);} \
;       } \
;     _Pragma("unroll") for(int r=0;r<16;++r)P0[r]=__builtin_amdgcn_exp2f(P0[r]); }while(0)
;   #define ROT() do{sl_prev=sl_cur;sl_cur=sl_next;sl_next=(sl_next==(NSLOT-1)*SLOTB)?0:sl_next+SLOTB;}while(0)
;   #define CMASK(P0,P1,t) do{}while(0)
;   #define CMASK(P0,P1,t) do{int jb_=(t)-(NT-4); if(jb_>=0)cmask(P0,P1,jb_,qrel,hi);}while(0)
; template<int THRL> __device__ __forceinline__ void attn_unit(int b,int h,int qb,unsigned char*wsb,char*shm,float kmax,const int CMB,float lam){
;     ...
;   const float mhat=sqrtf(q2_)*kmax*1.004f+0.02f;
;   float l_reg=0.f;f32x16 o[2];o[0]=f32x16{};o[1]=f32x16{};f32x16 o2[2];o2[0]=f32x16{};o2[1]=f32x16{};const f32x16 negm=f32x16{};
;   const int qrel=wid*QBLK+r32;
;     ...
;   bool resc=false;
;     ...
;   f32x16 pA0,pA1,pB0,pB1;
;   int sl_prev=0,sl_cur=0,sl_next=SLOTB;
;     ...
;   DMA_K(2,2*SLOTB);
;   WAIT_BAR(4);
;   qkt(pA0,pA1,Kbase,qr,negm,r32,hi);asm volatile("s_nop 15\n\ts_nop 7":"+v"(pA0),"+v"(pA1));CMASK(pA0,pA1,0);
;   START(pA0,pA1);
;   _Pragma("unroll") for(int r=0;r<16;++r)pA1[r]=__builtin_amdgcn_exp2f(pA1[r]);
;   WAIT_BAR(0);
;   DMA_K(3,0);DMA_V(1,SLOTB);
;   ROT();
;   kload8(kf,kp0+sl_cur);
;   WAIT_BAR(3);
.LBB0_309:
	v_mov_b32_e32 v39, s6
	v_add_f32_e32 v39, s5, v39
	v_mul_f32_e32 v40, 0x4f800000, v39
	v_cmp_gt_f32_e32 vcc, s74, v39
	v_add_f32_e32 v37, v37, v38
	v_mul_f32_e32 v38, 0x4f800000, v37
	v_cndmask_b32_e32 v39, v39, v40, vcc
	v_sqrt_f32_e32 v40, v39
	s_waitcnt vmcnt(0) lgkmcnt(0)
	s_barrier
	s_cmp_lg_u32 0, -1
	s_mov_b32 s37, 0
	v_add_u32_e32 v41, -1, v40
	v_fma_f32 v42, -v41, v40, v39
	v_cmp_ge_f32_e64 s[4:5], 0, v42
	v_add_u32_e32 v42, 1, v40
	s_mov_b32 s6, 1
	v_cndmask_b32_e64 v41, v40, v41, s[4:5]
	v_fma_f32 v40, -v42, v40, v39
	v_cmp_lt_f32_e64 s[4:5], 0, v40
	s_nop 1
	v_cndmask_b32_e64 v40, v41, v42, s[4:5]
	v_mul_f32_e32 v41, 0x37800000, v40
	v_cndmask_b32_e32 v40, v40, v41, vcc
	v_cmp_class_f32_e32 vcc, v39, v237
	s_nop 1
	v_cndmask_b32_e32 v39, v40, v39, vcc
	v_cmp_gt_f32_e32 vcc, s74, v37
	v_lshlrev_b32_e32 v40, 1, v36
	v_and_b32_e32 v251, 32, v40
	v_cndmask_b32_e32 v37, v37, v38, vcc
	v_sqrt_f32_e32 v38, v37
	v_lshlrev_b32_e32 v40, 4, v36
	v_and_b32_e32 v40, 0xc0, v40
	v_lshl_or_b32 v246, v242, 8, v40
	v_add_u32_e32 v40, 0, v251
	v_add3_u32 v252, v40, v249, v246
	v_add_u32_e32 v40, -1, v38
	v_fma_f32 v41, -v40, v38, v37
	v_cmp_ge_f32_e64 s[4:5], 0, v41
	v_add_u32_e32 v41, 1, v38
	v_mul_f32_e32 v39, 0x3f8147ae, v39
	v_cndmask_b32_e64 v40, v38, v40, s[4:5]
	v_fma_f32 v38, -v41, v38, v37
	v_cmp_lt_f32_e64 s[4:5], 0, v38
	s_nop 1
	v_cndmask_b32_e64 v38, v40, v41, s[4:5]
	v_mul_f32_e32 v40, 0x37800000, v38
	v_cndmask_b32_e32 v38, v38, v40, vcc
	v_cmp_class_f32_e32 vcc, v37, v237
	s_mov_b64 s[4:5], 0x60000
	s_nop 0
	v_cndmask_b32_e32 v37, v38, v37, vcc
	v_mul_f32_e32 v37, v39, v37
	v_fmamk_f32 v247, v37, 0x3f808312, v238
	v_sub_f32_e32 v0, v0, v247
	v_sub_f32_e32 v1, v1, v247
	v_sub_f32_e32 v16, v16, v247
	v_sub_f32_e32 v17, v17, v247
	v_sub_f32_e32 v2, v2, v247
	v_sub_f32_e32 v18, v18, v247
	s_nop 0
	v_exp_f32_e32 v96, v0
	v_exp_f32_e32 v97, v1
	v_lshl_add_u64 v[0:1], v[32:33], 0, s[4:5]
	s_mov_b32 s4, m0
	s_mov_b32 m0, s3
	s_nop 0
	global_load_lds_dwordx4 v[0:1], off
	s_mov_b32 m0, s4
	s_mov_b64 s[4:5], 0x20000
	v_lshl_add_u64 v[0:1], v[34:35], 0, s[4:5]
	s_cselect_b32 s4, 0, 0
	s_add_i32 s1, s4, s1
	s_add_i32 s4, s1, 0x8000
	s_mov_b32 s5, m0
	s_mov_b32 m0, s4
	s_nop 0
	global_load_lds_dwordx4 v[0:1], off
	s_mov_b32 m0, s5
	s_mov_b64 s[4:5], 0x20080
	v_lshl_add_u64 v[0:1], v[34:35], 0, s[4:5]
	s_add_i32 s1, s1, 0xe000
	s_mov_b32 s4, m0
	s_mov_b32 m0, s1
	s_nop 0
	global_load_lds_dwordx4 v[0:1], off
	s_mov_b32 m0, s4
	ds_read_b128 v[204:207], v250 offset:8192
	ds_read_b128 v[200:203], v250 offset:8704
	ds_read_b128 v[196:199], v250 offset:10240
	ds_read_b128 v[192:195], v250 offset:10752
	ds_read_b128 v[188:191], v250 offset:12288
	ds_read_b128 v[184:187], v250 offset:12800
	ds_read_b128 v[180:183], v250 offset:14336
	ds_read_b128 v[176:179], v250 offset:14848
	v_sub_f32_e32 v3, v3, v247
	v_sub_f32_e32 v19, v19, v247
	v_sub_f32_e32 v4, v4, v247
	v_sub_f32_e32 v20, v20, v247
	v_sub_f32_e32 v5, v5, v247
	v_sub_f32_e32 v21, v21, v247
	v_sub_f32_e32 v6, v6, v247
	v_sub_f32_e32 v22, v22, v247
	v_sub_f32_e32 v7, v7, v247
	v_sub_f32_e32 v23, v23, v247
	v_sub_f32_e32 v8, v8, v247
	v_sub_f32_e32 v24, v24, v247
	v_sub_f32_e32 v9, v9, v247
	v_sub_f32_e32 v25, v25, v247
	v_sub_f32_e32 v10, v10, v247
	v_sub_f32_e32 v26, v26, v247
	v_sub_f32_e32 v11, v11, v247
	v_sub_f32_e32 v27, v27, v247
	v_sub_f32_e32 v12, v12, v247
	v_sub_f32_e32 v28, v28, v247
	v_sub_f32_e32 v13, v13, v247
	v_sub_f32_e32 v29, v29, v247
	v_sub_f32_e32 v14, v14, v247
	v_sub_f32_e32 v30, v30, v247
	v_sub_f32_e32 v15, v15, v247
	v_sub_f32_e32 v31, v31, v247
	v_exp_f32_e32 v98, v2
	v_exp_f32_e32 v99, v3
	v_exp_f32_e32 v100, v4
	v_exp_f32_e32 v101, v5
	v_exp_f32_e32 v102, v6
	v_exp_f32_e32 v103, v7
	v_exp_f32_e32 v104, v8
	v_exp_f32_e32 v105, v9
	v_exp_f32_e32 v106, v10
	v_exp_f32_e32 v107, v11
	v_exp_f32_e32 v108, v12
	v_exp_f32_e32 v109, v13
	v_exp_f32_e32 v110, v14
	v_exp_f32_e32 v111, v15
	v_exp_f32_e32 v80, v16
	v_exp_f32_e32 v81, v17
	v_exp_f32_e32 v82, v18
	v_exp_f32_e32 v83, v19
	v_exp_f32_e32 v84, v20
	v_exp_f32_e32 v85, v21
	v_exp_f32_e32 v86, v22
	v_exp_f32_e32 v87, v23
	v_exp_f32_e32 v88, v24
	v_exp_f32_e32 v89, v25
	v_exp_f32_e32 v90, v26
	v_exp_f32_e32 v91, v27
	v_exp_f32_e32 v92, v28
	v_exp_f32_e32 v93, v29
	v_exp_f32_e32 v94, v30
	v_exp_f32_e32 v95, v31
	s_waitcnt vmcnt(3) lgkmcnt(0)
	s_barrier
	v_and_b32_e32 v0, 3, v36
	s_andn2_b64 vcc, exec, s[54:55]
	v_lshlrev_b32_e32 v208, 4, v0
	s_cbranch_vccnz .LBB0_313
; template<int THRL> __device__ __forceinline__ void attn_unit(int b,int h,int qb,unsigned char*wsb,char*shm,float kmax,const int CMB,float lam){
;     ...
;   float l_reg=0.f;f32x16 o[2];o[0]=f32x16{};o[1]=f32x16{};f32x16 o2[2];o2[0]=f32x16{};o2[1]=f32x16{};const f32x16 negm=f32x16{};
;   const int qrel=wid*QBLK+r32;
;     ...
;   bool resc=false;
;     ...
;   f32x16 pA0,pA1,pB0,pB1;
;   int sl_prev=0,sl_cur=0,sl_next=SLOTB;
	s_lshl_b32 s1, s43, 6
	s_add_i32 s6, s79, s1
	s_lshr_b32 s4, s6, 7
	s_mov_b32 s5, s7
	s_lshl_b64 s[4:5], s[4:5], 8
	s_lshl_b64 s[36:37], s[68:69], 1
	s_add_u32 s4, s36, s4
	v_mov_b32_e32 v209, v221
	s_addc_u32 s5, s37, s5
	s_lshl_b32 s1, s95, 9
	v_lshl_add_u64 v[0:1], s[4:5], 0, v[208:209]
	s_and_b32 s1, s1, 0x18000
	s_lshl_b64 s[4:5], s[66:67], 1
	s_lshl_b64 s[36:37], s[6:7], 1
	v_lshl_or_b32 v2, v214, 11, s1
	s_add_u32 s1, s64, s36
	s_addc_u32 s6, s65, s37
	v_mov_b32_e32 v3, v221
	s_add_u32 s4, s1, s4
	v_lshl_add_u64 v[0:1], v[0:1], 0, v[2:3]
	s_addc_u32 s5, s6, s5
	v_mov_b32_e32 v64, 0
	s_mov_b32 s33, 6
	v_lshl_add_u64 v[210:211], s[64:65], 0, v[0:1]
	v_lshl_add_u64 v[212:213], s[4:5], 0, v[220:221]
	s_movk_i32 s36, 0x4000
	s_movk_i32 s42, 0x2000
	s_mov_b32 s5, 0
	v_mov_b32_e32 v0, 0
	v_mov_b32_e32 v1, v64
	v_mov_b32_e32 v2, v64
	v_mov_b32_e32 v3, v64
	v_mov_b32_e32 v4, v64
	v_mov_b32_e32 v5, v64
	v_mov_b32_e32 v6, v64
	v_mov_b32_e32 v7, v64
	v_mov_b32_e32 v8, v64
	v_mov_b32_e32 v9, v64
	v_mov_b32_e32 v10, v64
	v_mov_b32_e32 v11, v64
	v_mov_b32_e32 v12, v64
	v_mov_b32_e32 v13, v64
	v_mov_b32_e32 v14, v64
	v_mov_b32_e32 v15, v64
	v_mov_b32_e32 v16, 0
	v_mov_b32_e32 v17, v64
	v_mov_b32_e32 v18, v64
	v_mov_b32_e32 v19, v64
	v_mov_b32_e32 v20, v64
	v_mov_b32_e32 v21, v64
	v_mov_b32_e32 v22, v64
	v_mov_b32_e32 v23, v64
	v_mov_b32_e32 v24, v64
	v_mov_b32_e32 v25, v64
	v_mov_b32_e32 v26, v64
	v_mov_b32_e32 v27, v64
	v_mov_b32_e32 v28, v64
	v_mov_b32_e32 v29, v64
	v_mov_b32_e32 v30, v64
	v_mov_b32_e32 v31, v64
	v_mov_b32_e32 v32, 0
	v_mov_b32_e32 v33, v64
	v_mov_b32_e32 v34, v64
	v_mov_b32_e32 v35, v64
	v_mov_b32_e32 v36, v64
	v_mov_b32_e32 v37, v64
	v_mov_b32_e32 v38, v64
	v_mov_b32_e32 v39, v64
	v_mov_b32_e32 v40, v64
	v_mov_b32_e32 v41, v64
	v_mov_b32_e32 v42, v64
	v_mov_b32_e32 v43, v64
	v_mov_b32_e32 v44, v64
	v_mov_b32_e32 v45, v64
	v_mov_b32_e32 v46, v64
	v_mov_b32_e32 v47, v64
	v_mov_b32_e32 v48, 0
	v_mov_b32_e32 v49, v64
	v_mov_b32_e32 v50, v64
	v_mov_b32_e32 v51, v64
	v_mov_b32_e32 v52, v64
	v_mov_b32_e32 v53, v64
	v_mov_b32_e32 v54, v64
	v_mov_b32_e32 v55, v64
	v_mov_b32_e32 v56, v64
	v_mov_b32_e32 v57, v64
	v_mov_b32_e32 v58, v64
	v_mov_b32_e32 v59, v64
	v_mov_b32_e32 v60, v64
	v_mov_b32_e32 v61, v64
	v_mov_b32_e32 v62, v64
	v_mov_b32_e32 v63, v64
	v_lshlrev_b32_e32 v143, 2, v230
	v_add_u32_e32 v143, 0x12800, v143
	ds_write_b32 v143, v246 offset:32768
	ds_write_b32 v143, v230
	ds_write_b32 v143, v231 offset:2048
	ds_write_b32 v143, v232 offset:4096
	ds_write_b32 v143, v233 offset:6144
	ds_write_b32 v143, v234 offset:8192
	ds_write_b32 v143, v235 offset:10240
	ds_write_b32 v143, v236 offset:12288
	ds_write_b32 v143, v237 offset:14336
	ds_write_b32 v143, v238 offset:16384
	ds_write_b32 v143, v239 offset:18432
	ds_write_b32 v143, v240 offset:20480
	ds_write_b32 v143, v241 offset:22528
	ds_write_b32 v143, v242 offset:24576
	ds_write_b32 v143, v243 offset:26624
	ds_write_b32 v143, v244 offset:28672
	ds_write_b32 v143, v245 offset:30720
	v_mov_b32_e32 v246, v143
	v_xor_b32_e32 v230, 0x80000000, v247
	v_mov_b32_e32 v231, v230
	v_mov_b32_e32 v232, v230
	v_mov_b32_e32 v233, v230
	v_mov_b32_e32 v234, v230
	v_mov_b32_e32 v235, v230
	v_mov_b32_e32 v236, v230
	v_mov_b32_e32 v237, v230
	v_mov_b32_e32 v238, v230
	v_mov_b32_e32 v239, v230
	v_mov_b32_e32 v240, v230
	v_mov_b32_e32 v241, v230
	v_mov_b32_e32 v242, v230
	v_mov_b32_e32 v243, v230
	v_mov_b32_e32 v244, v230
	v_mov_b32_e32 v245, v230
	s_waitcnt lgkmcnt(0)
	s_nop 0
	s_nop 0
	s_nop 0
	s_nop 0
	s_nop 0
	s_nop 0
	s_nop 0
	s_nop 0
	s_nop 0
	s_nop 0
	s_nop 0
	s_nop 0
	s_nop 0
	s_nop 0
.LBB0_311:
	s_mov_b32 s37, s36
	s_mov_b32 s4, s33
	s_mov_b32 s1, s42
	v_add_u32_e32 v209, s5, v252
	ds_read_b64_tr_b16 v[216:217], v209 offset:24576
	ds_read_b64_tr_b16 v[218:219], v209 offset:25088
	v_add_f32_e32 v65, v96, v97
	v_add_f32_e32 v65, v98, v65
	v_add_f32_e32 v65, v99, v65
	v_add_f32_e32 v65, v100, v65
	v_add_f32_e32 v65, v101, v65
	v_cvt_pk_bf16_f32 v172, v96, v97
	v_cvt_pk_bf16_f32 v173, v98, v99
	s_waitcnt lgkmcnt(9)
	v_mfma_f32_32x32x16_bf16 v[128:143], v[204:207], v[156:159], v[230:245]
	ds_read_b64_tr_b16 v[204:205], v209 offset:28672
	ds_read_b64_tr_b16 v[206:207], v209 offset:29184
	v_add_f32_e32 v65, v102, v65
	v_add_f32_e32 v65, v103, v65
	v_add_f32_e32 v65, v104, v65
	v_add_f32_e32 v65, v105, v65
	v_cvt_pk_bf16_f32 v174, v100, v101
	v_cvt_pk_bf16_f32 v175, v102, v103
	s_waitcnt lgkmcnt(10)
	v_mfma_f32_32x32x16_bf16 v[112:127], v[200:203], v[156:159], v[230:245]
	ds_read_b64_tr_b16 v[74:75], v209 offset:25600
	ds_read_b64_tr_b16 v[76:77], v209 offset:26112
	v_add_f32_e32 v65, v106, v65
	v_add_f32_e32 v65, v107, v65
	v_add_f32_e32 v65, v108, v65
	v_add_f32_e32 v65, v109, v65
	v_cvt_pk_bf16_f32 v168, v104, v105
	v_cvt_pk_bf16_f32 v169, v106, v107
	s_waitcnt lgkmcnt(11)
	v_mfma_f32_32x32x16_bf16 v[128:143], v[196:199], v[152:155], v[128:143]
	ds_read_b64_tr_b16 v[70:71], v209 offset:29696
	ds_read_b64_tr_b16 v[72:73], v209 offset:30208
	v_add_f32_e32 v65, v110, v65
	v_add_f32_e32 v65, v111, v65
	v_add_f32_e32 v65, v80, v65
	v_add_f32_e32 v65, v81, v65
	v_cvt_pk_bf16_f32 v170, v108, v109
	v_cvt_pk_bf16_f32 v171, v110, v111
	s_waitcnt lgkmcnt(12)
	v_mfma_f32_32x32x16_bf16 v[112:127], v[192:195], v[152:155], v[112:127]
	ds_read_b64_tr_b16 v[66:67], v209 offset:26624
	ds_read_b64_tr_b16 v[68:69], v209 offset:27136
	v_add_f32_e32 v65, v82, v65
	v_add_f32_e32 v65, v83, v65
	v_add_f32_e32 v65, v84, v65
	v_add_f32_e32 v65, v85, v65
	v_cvt_pk_bf16_f32 v164, v80, v81
	v_cvt_pk_bf16_f32 v165, v82, v83
	s_waitcnt lgkmcnt(13)
	v_mfma_f32_32x32x16_bf16 v[128:143], v[188:191], v[148:151], v[128:143]
	ds_read_b64_tr_b16 v[100:101], v209 offset:30720
	ds_read_b64_tr_b16 v[102:103], v209 offset:31232
	v_add_f32_e32 v65, v86, v65
	v_add_f32_e32 v65, v87, v65
	v_add_f32_e32 v65, v88, v65
	v_add_f32_e32 v65, v89, v65
	v_cvt_pk_bf16_f32 v166, v84, v85
	v_cvt_pk_bf16_f32 v167, v86, v87
	s_waitcnt lgkmcnt(14)
	v_mfma_f32_32x32x16_bf16 v[112:127], v[184:187], v[148:151], v[112:127]
	ds_read_b64_tr_b16 v[96:97], v209 offset:27648
	ds_read_b64_tr_b16 v[98:99], v209 offset:28160
	v_add_f32_e32 v65, v90, v65
	v_add_f32_e32 v65, v91, v65
	v_add_f32_e32 v65, v92, v65
	v_add_f32_e32 v65, v93, v65
	v_cvt_pk_bf16_f32 v160, v88, v89
	v_cvt_pk_bf16_f32 v161, v90, v91
	s_waitcnt lgkmcnt(14)
	v_mfma_f32_32x32x16_bf16 v[128:143], v[180:183], v[144:147], v[128:143]
	ds_read_b64_tr_b16 v[86:87], v209 offset:31744
	ds_read_b64_tr_b16 v[88:89], v209 offset:32256
	v_add_f32_e32 v65, v94, v65
	v_add_f32_e32 v65, v95, v65
	v_add_f32_e32 v65, 0, v65
	v_cvt_pk_bf16_f32 v162, v92, v93
	v_cvt_pk_bf16_f32 v163, v94, v95
	v_mfma_f32_32x32x16_bf16 v[112:127], v[176:179], v[144:147], v[112:127]
	v_lshl_add_u64 v[190:191], v[212:213], 0, s[48:49]
	v_lshl_add_u64 v[78:79], v[190:191], 0, s[10:11]
	s_add_i32 s5, s42, s3
	s_mov_b32 s6, m0
	s_mov_b32 m0, s5
	s_nop 0
	global_load_lds_dwordx4 v[78:79], off
	s_mov_b32 m0, s6
	v_lshl_add_u64 v[188:189], v[210:211], 0, s[48:49]
	v_lshl_add_u64 v[78:79], v[188:189], 0, s[12:13]
	s_add_i32 s5, s36, s97
	s_mov_b32 s6, m0
	s_mov_b32 m0, s5
	s_nop 0
	global_load_lds_dwordx4 v[78:79], off
	s_mov_b32 m0, s6
	v_lshl_add_u64 v[78:79], v[188:189], 0, s[14:15]
	s_add_i32 s5, s36, s96
	s_mov_b32 s6, m0
	s_mov_b32 m0, s5
	s_nop 0
	global_load_lds_dwordx4 v[78:79], off
	s_mov_b32 m0, s6
	s_waitcnt lgkmcnt(14)
	v_mfma_f32_32x32x16_bf16 v[32:47], v[172:175], v[216:219], v[32:47]
	v_exp_f32_e32 v128, v128
	v_exp_f32_e32 v129, v129
	ds_read_b64_tr_b16 v[90:91], v209 offset:49152
	ds_read_b64_tr_b16 v[92:93], v209 offset:49664
	s_waitcnt lgkmcnt(14)
	v_mfma_f32_32x32x16_bf16 v[48:63], v[172:175], v[204:207], v[48:63]
	v_exp_f32_e32 v130, v130
	v_exp_f32_e32 v131, v131
	ds_read_b64_tr_b16 v[104:105], v209 offset:53248
	ds_read_b64_tr_b16 v[106:107], v209 offset:53760
	v_add_u32_e32 v94, s37, v250
	ds_read_b128 v[82:85], v94
	ds_read_b128 v[78:81], v94 offset:512
	s_waitcnt lgkmcnt(14)
	v_mfma_f32_32x32x16_bf16 v[32:47], v[168:171], v[74:77], v[32:47]
	v_exp_f32_e32 v132, v132
	v_exp_f32_e32 v133, v133
	ds_read_b64_tr_b16 v[108:109], v209 offset:50176
	ds_read_b64_tr_b16 v[110:111], v209 offset:50688
	ds_read_b128 v[184:187], v94 offset:2048
	ds_read_b128 v[176:179], v94 offset:2560
	v_mfma_f32_32x32x16_bf16 v[48:63], v[168:171], v[70:73], v[48:63]
	v_exp_f32_e32 v134, v134
	v_exp_f32_e32 v135, v135
	ds_read_b64_tr_b16 v[192:193], v209 offset:54272
	ds_read_b64_tr_b16 v[194:195], v209 offset:54784
	ds_read_b128 v[180:183], v94 offset:4096
	ds_read_b128 v[70:73], v94 offset:4608
	s_waitcnt lgkmcnt(14)
	v_mfma_f32_32x32x16_bf16 v[32:47], v[164:167], v[66:69], v[32:47]
	v_exp_f32_e32 v136, v136
	v_exp_f32_e32 v137, v137
	ds_read_b64_tr_b16 v[196:197], v209 offset:51200
	ds_read_b64_tr_b16 v[198:199], v209 offset:51712
	ds_read_b128 v[74:77], v94 offset:6144
	ds_read_b128 v[66:69], v94 offset:6656
	v_mfma_f32_32x32x16_bf16 v[48:63], v[164:167], v[100:103], v[48:63]
	v_exp_f32_e32 v138, v138
	v_exp_f32_e32 v139, v139
	ds_read_b64_tr_b16 v[100:101], v209 offset:55296
	ds_read_b64_tr_b16 v[102:103], v209 offset:55808
	v_mfma_f32_32x32x16_bf16 v[32:47], v[160:163], v[96:99], v[32:47]
	v_exp_f32_e32 v140, v140
	v_exp_f32_e32 v141, v141
	ds_read_b64_tr_b16 v[94:95], v209 offset:52224
	ds_read_b64_tr_b16 v[96:97], v209 offset:52736
	v_mfma_f32_32x32x16_bf16 v[48:63], v[160:163], v[86:89], v[48:63]
	v_exp_f32_e32 v142, v142
	v_exp_f32_e32 v143, v143
	ds_read_b64_tr_b16 v[86:87], v209 offset:56320
	ds_read_b64_tr_b16 v[88:89], v209 offset:56832
	s_waitcnt lgkmcnt(14)
	v_mfma_f32_32x32x16_bf16 v[0:15], v[172:175], v[90:93], v[0:15]
	v_exp_f32_e32 v112, v112
	v_exp_f32_e32 v113, v113
	v_mfma_f32_32x32x16_bf16 v[16:31], v[172:175], v[104:107], v[16:31]
	v_exp_f32_e32 v114, v114
	v_exp_f32_e32 v115, v115
	v_mfma_f32_32x32x16_bf16 v[0:15], v[168:171], v[108:111], v[0:15]
	v_exp_f32_e32 v116, v116
	v_exp_f32_e32 v117, v117
	s_waitcnt lgkmcnt(12)
	v_mfma_f32_32x32x16_bf16 v[16:31], v[168:171], v[192:195], v[16:31]
	v_exp_f32_e32 v118, v118
	v_exp_f32_e32 v119, v119
	s_waitcnt lgkmcnt(8)
	v_mfma_f32_32x32x16_bf16 v[0:15], v[164:167], v[196:199], v[0:15]
	v_exp_f32_e32 v120, v120
	v_exp_f32_e32 v121, v121
	s_waitcnt lgkmcnt(4)
	v_mfma_f32_32x32x16_bf16 v[16:31], v[164:167], v[100:103], v[16:31]
	v_exp_f32_e32 v122, v122
	v_exp_f32_e32 v123, v123
	s_waitcnt lgkmcnt(2)
	v_mfma_f32_32x32x16_bf16 v[0:15], v[160:163], v[94:97], v[0:15]
	v_exp_f32_e32 v124, v124
	v_exp_f32_e32 v125, v125
	s_waitcnt lgkmcnt(0)
	v_mfma_f32_32x32x16_bf16 v[16:31], v[160:163], v[86:89], v[16:31]
	v_exp_f32_e32 v126, v126
	v_exp_f32_e32 v127, v127
	s_waitcnt vmcnt(3) lgkmcnt(0)
	s_barrier
; #define WAIT_BAR(N) asm volatile("s_waitcnt vmcnt(" #N ") lgkmcnt(0)\n\ts_barrier":::"memory")
;   #define RESC() do{ if(resc){ asm volatile("s_waitcnt lgkmcnt(0)":::"memory"); \
;       _Pragma("unroll") for(int d_=0;d_<2;++d_) _Pragma("unroll") for(int r=0;r<16;++r){const float f_=wsf[crow(r,hi)];o[d_][r]*=f_;o2[d_][r]*=f_;} } }while(0)
;   #define ROT() do{sl_prev=sl_cur;sl_cur=sl_next;sl_next=(sl_next==(NSLOT-1)*SLOTB)?0:sl_next+SLOTB;}while(0)
; template<int THRL> __device__ __forceinline__ void attn_unit(int b,int h,int qb,unsigned char*wsb,char*shm,float kmax,const int CMB,float lam){
;     ...
;   int t=1;
;     ...
;   for(;t+5<NT;t+=2){
;     STEP(pB0,pB1,pA0,pA1,t,true,true,true);     WAIT_BAR(3); RESC(); ROT();
;     STEP(pA0,pA1,pB0,pB1,t+1,true,true,true);   WAIT_BAR(3); RESC(); ROT();
	s_add_i32 s5, s36, 0x2000
	s_cmpk_lg_i32 s36, 0x4000
	s_cselect_b32 s42, s5, 0
	v_add_u32_e32 v209, s1, v252
	ds_read_b64_tr_b16 v[192:193], v209 offset:24576
	ds_read_b64_tr_b16 v[194:195], v209 offset:25088
	v_mfma_f32_32x32x16_bf16 v[96:111], v[82:85], v[156:159], v[230:245]
	v_add_f32_e32 v86, v128, v129
	v_add_f32_e32 v86, v130, v86
	v_add_f32_e32 v86, v131, v86
	v_add_f32_e32 v86, v132, v86
	v_add_f32_e32 v86, v133, v86
	v_cvt_pk_bf16_f32 v172, v128, v129
	v_cvt_pk_bf16_f32 v173, v130, v131
	ds_read_b64_tr_b16 v[196:197], v209 offset:28672
	ds_read_b64_tr_b16 v[198:199], v209 offset:29184
	v_add_f32_e32 v82, v134, v86
	v_add_f32_e32 v82, v135, v82
	v_add_f32_e32 v82, v136, v82
	v_add_f32_e32 v128, v137, v82
	v_mfma_f32_32x32x16_bf16 v[80:95], v[78:81], v[156:159], v[230:245]
	v_cvt_pk_bf16_f32 v174, v132, v133
	v_cvt_pk_bf16_f32 v175, v134, v135
	ds_read_b64_tr_b16 v[216:217], v209 offset:25600
	ds_read_b64_tr_b16 v[218:219], v209 offset:26112
	v_mfma_f32_32x32x16_bf16 v[96:111], v[184:187], v[152:155], v[96:111]
	v_add_f32_e32 v78, v138, v128
	v_add_f32_e32 v78, v139, v78
	v_add_f32_e32 v78, v140, v78
	v_add_f32_e32 v78, v141, v78
	v_cvt_pk_bf16_f32 v168, v136, v137
	v_cvt_pk_bf16_f32 v169, v138, v139
	ds_read_b64_tr_b16 v[136:137], v209 offset:29696
	ds_read_b64_tr_b16 v[138:139], v209 offset:30208
	v_mfma_f32_32x32x16_bf16 v[80:95], v[176:179], v[152:155], v[80:95]
	v_add_f32_e32 v78, v142, v78
	v_add_f32_e32 v78, v143, v78
	v_add_f32_e32 v78, v112, v78
	v_add_f32_e32 v78, v113, v78
	v_cvt_pk_bf16_f32 v170, v140, v141
	v_cvt_pk_bf16_f32 v171, v142, v143
	ds_read_b64_tr_b16 v[132:133], v209 offset:26624
	ds_read_b64_tr_b16 v[134:135], v209 offset:27136
	v_mfma_f32_32x32x16_bf16 v[96:111], v[180:183], v[148:151], v[96:111]
	v_add_f32_e32 v78, v114, v78
	v_add_f32_e32 v78, v115, v78
	v_add_f32_e32 v78, v116, v78
	v_add_f32_e32 v78, v117, v78
	v_cvt_pk_bf16_f32 v164, v112, v113
	v_cvt_pk_bf16_f32 v165, v114, v115
	ds_read_b64_tr_b16 v[128:129], v209 offset:30720
	ds_read_b64_tr_b16 v[130:131], v209 offset:31232
	v_mfma_f32_32x32x16_bf16 v[80:95], v[70:73], v[148:151], v[80:95]
	v_add_f32_e32 v78, v118, v78
	v_add_f32_e32 v78, v119, v78
	v_add_f32_e32 v78, v120, v78
	v_add_f32_e32 v78, v121, v78
	v_cvt_pk_bf16_f32 v166, v116, v117
	v_cvt_pk_bf16_f32 v167, v118, v119
	ds_read_b64_tr_b16 v[112:113], v209 offset:27648
	ds_read_b64_tr_b16 v[114:115], v209 offset:28160
	v_mfma_f32_32x32x16_bf16 v[96:111], v[74:77], v[144:147], v[96:111]
	v_add_f32_e32 v70, v122, v78
	v_add_f32_e32 v70, v123, v70
	v_add_f32_e32 v70, v124, v70
	v_add_f32_e32 v78, v125, v70
	v_cvt_pk_bf16_f32 v160, v120, v121
	v_cvt_pk_bf16_f32 v161, v122, v123
	ds_read_b64_tr_b16 v[70:71], v209 offset:31744
	ds_read_b64_tr_b16 v[72:73], v209 offset:32256
	v_mfma_f32_32x32x16_bf16 v[80:95], v[66:69], v[144:147], v[80:95]
	v_add_f32_e32 v74, v126, v78
	v_add_f32_e32 v74, v127, v74
	v_add_f32_e32 v74, 0, v74
	v_cvt_pk_bf16_f32 v162, v124, v125
	v_cvt_pk_bf16_f32 v163, v126, v127
	v_lshl_add_u64 v[66:67], v[190:191], 0, s[16:17]
	s_add_i32 s1, s36, s3
	s_mov_b32 s5, m0
	s_mov_b32 m0, s1
	s_nop 0
	global_load_lds_dwordx4 v[66:67], off
	s_mov_b32 m0, s5
	v_lshl_add_u64 v[66:67], v[188:189], 0, s[18:19]
	s_add_i32 s1, s42, s97
	s_mov_b32 s5, m0
	s_mov_b32 m0, s1
	s_nop 0
	global_load_lds_dwordx4 v[66:67], off
	s_mov_b32 m0, s5
	v_lshl_add_u64 v[66:67], v[188:189], 0, s[20:21]
	s_add_i32 s1, s42, s96
	s_mov_b32 s5, m0
	s_mov_b32 m0, s1
	s_nop 0
	global_load_lds_dwordx4 v[66:67], off
	s_mov_b32 m0, s5
	s_waitcnt lgkmcnt(14)
	v_mfma_f32_32x32x16_bf16 v[32:47], v[172:175], v[192:195], v[32:47]
	v_exp_f32_e32 v96, v96
	v_exp_f32_e32 v97, v97
	ds_read_b64_tr_b16 v[66:67], v209 offset:49152
	ds_read_b64_tr_b16 v[68:69], v209 offset:49664
	s_waitcnt lgkmcnt(14)
	v_mfma_f32_32x32x16_bf16 v[48:63], v[172:175], v[196:199], v[48:63]
	v_exp_f32_e32 v98, v98
	v_exp_f32_e32 v99, v99
	ds_read_b64_tr_b16 v[76:77], v209 offset:53248
	ds_read_b64_tr_b16 v[78:79], v209 offset:53760
	v_add_u32_e32 v75, s42, v250
	ds_read_b128 v[204:207], v75
	ds_read_b128 v[200:203], v75 offset:512
	s_waitcnt lgkmcnt(14)
	v_mfma_f32_32x32x16_bf16 v[32:47], v[168:171], v[216:219], v[32:47]
	v_exp_f32_e32 v100, v100
	v_exp_f32_e32 v101, v101
	ds_read_b64_tr_b16 v[116:117], v209 offset:50176
	ds_read_b64_tr_b16 v[118:119], v209 offset:50688
	ds_read_b128 v[196:199], v75 offset:2048
	ds_read_b128 v[192:195], v75 offset:2560
	v_mfma_f32_32x32x16_bf16 v[48:63], v[168:171], v[136:139], v[48:63]
	v_exp_f32_e32 v102, v102
	v_exp_f32_e32 v103, v103
	ds_read_b64_tr_b16 v[120:121], v209 offset:54272
	ds_read_b64_tr_b16 v[122:123], v209 offset:54784
	ds_read_b128 v[188:191], v75 offset:4096
	ds_read_b128 v[184:187], v75 offset:4608
	s_waitcnt lgkmcnt(14)
	v_mfma_f32_32x32x16_bf16 v[32:47], v[164:167], v[132:135], v[32:47]
	v_exp_f32_e32 v104, v104
	v_exp_f32_e32 v105, v105
	ds_read_b64_tr_b16 v[124:125], v209 offset:51200
	ds_read_b64_tr_b16 v[126:127], v209 offset:51712
	ds_read_b128 v[180:183], v75 offset:6144
	ds_read_b128 v[176:179], v75 offset:6656
	v_mfma_f32_32x32x16_bf16 v[48:63], v[164:167], v[128:131], v[48:63]
	v_exp_f32_e32 v106, v106
	v_exp_f32_e32 v107, v107
	ds_read_b64_tr_b16 v[128:129], v209 offset:55296
	ds_read_b64_tr_b16 v[130:131], v209 offset:55808
	v_mfma_f32_32x32x16_bf16 v[32:47], v[160:163], v[112:115], v[32:47]
	v_exp_f32_e32 v108, v108
	v_exp_f32_e32 v109, v109
	ds_read_b64_tr_b16 v[112:113], v209 offset:52224
	ds_read_b64_tr_b16 v[114:115], v209 offset:52736
	v_mfma_f32_32x32x16_bf16 v[48:63], v[160:163], v[70:73], v[48:63]
	v_exp_f32_e32 v110, v110
	v_exp_f32_e32 v111, v111
	ds_read_b64_tr_b16 v[70:71], v209 offset:56320
	ds_read_b64_tr_b16 v[72:73], v209 offset:56832
	s_waitcnt lgkmcnt(14)
	v_mfma_f32_32x32x16_bf16 v[0:15], v[172:175], v[66:69], v[0:15]
	v_exp_f32_e32 v80, v80
	v_exp_f32_e32 v81, v81
	v_mfma_f32_32x32x16_bf16 v[16:31], v[172:175], v[76:79], v[16:31]
	v_exp_f32_e32 v82, v82
	v_exp_f32_e32 v83, v83
	v_mfma_f32_32x32x16_bf16 v[0:15], v[168:171], v[116:119], v[0:15]
	v_exp_f32_e32 v84, v84
	v_exp_f32_e32 v85, v85
	s_waitcnt lgkmcnt(12)
	v_mfma_f32_32x32x16_bf16 v[16:31], v[168:171], v[120:123], v[16:31]
	v_exp_f32_e32 v86, v86
	v_exp_f32_e32 v87, v87
	s_waitcnt lgkmcnt(8)
	v_mfma_f32_32x32x16_bf16 v[0:15], v[164:167], v[124:127], v[0:15]
	v_exp_f32_e32 v88, v88
	v_exp_f32_e32 v89, v89
	s_waitcnt lgkmcnt(4)
	v_mfma_f32_32x32x16_bf16 v[16:31], v[164:167], v[128:131], v[16:31]
	v_exp_f32_e32 v90, v90
	v_exp_f32_e32 v91, v91
	s_waitcnt lgkmcnt(2)
	v_mfma_f32_32x32x16_bf16 v[0:15], v[160:163], v[112:115], v[0:15]
	v_exp_f32_e32 v92, v92
	v_exp_f32_e32 v93, v93
	s_waitcnt lgkmcnt(0)
	v_mfma_f32_32x32x16_bf16 v[16:31], v[160:163], v[70:73], v[16:31]
	v_exp_f32_e32 v94, v94
	v_exp_f32_e32 v95, v95
	s_add_i32 s1, s42, 0x2000
	s_waitcnt vmcnt(3) lgkmcnt(0)
	s_barrier
; #define WAIT_BAR(N) asm volatile("s_waitcnt vmcnt(" #N ") lgkmcnt(0)\n\ts_barrier":::"memory")
;   #define RESC() do{ if(resc){ asm volatile("s_waitcnt lgkmcnt(0)":::"memory"); \
;       _Pragma("unroll") for(int d_=0;d_<2;++d_) _Pragma("unroll") for(int r=0;r<16;++r){const float f_=wsf[crow(r,hi)];o[d_][r]*=f_;o2[d_][r]*=f_;} } }while(0)
;   #define ROT() do{sl_prev=sl_cur;sl_cur=sl_next;sl_next=(sl_next==(NSLOT-1)*SLOTB)?0:sl_next+SLOTB;}while(0)
;   #define ENDW(tt) do{ if((tt)+3<NT){WAIT_BAR(3);} else if((tt)+2<NT){WAIT_BAR(2);} else {WAIT_BAR(0);} }while(0)
; template<int THRL> __device__ __forceinline__ void attn_unit(int b,int h,int qb,unsigned char*wsb,char*shm,float kmax,const int CMB,float lam){
;     ...
;   for(;t+5<NT;t+=2){
;     STEP(pB0,pB1,pA0,pA1,t,true,true,true);     WAIT_BAR(3); RESC(); ROT();
;     STEP(pA0,pA1,pB0,pB1,t+1,true,true,true);   WAIT_BAR(3); RESC(); ROT();
;   }
;     ...
;   for(;t+1<NT;t+=2){
;     STEP(pB0,pB1,pA0,pA1,t,(t+3<NT),(t+1<NT),(t+1<NT));       ENDW(t);   RESC(); ROT();
;     STEP(pA0,pA1,pB0,pB1,t+1,(t+4<NT),(t+2<NT),(t+2<NT));     ENDW(t+1); RESC(); ROT();
;   }
	s_cmpk_lg_i32 s42, 0x4000
	v_add_f32_e32 v64, v64, v65
	s_mov_b32 s5, s36
	s_cselect_b32 s36, s1, 0
	s_add_i32 s33, s33, 2
	v_lshl_add_u64 v[210:211], v[210:211], 0, s[22:23]
	v_lshl_add_u64 v[212:213], v[212:213], 0, s[22:23]
	s_cmp_ge_u32 s33, s89
	v_add_f32_e32 v64, v64, v74
	s_cbranch_scc0 .LBB0_311
	ds_read_b32 v230, v246
	ds_read_b32 v231, v246 offset:2048
	ds_read_b32 v232, v246 offset:4096
	ds_read_b32 v233, v246 offset:6144
	ds_read_b32 v234, v246 offset:8192
	ds_read_b32 v235, v246 offset:10240
	ds_read_b32 v236, v246 offset:12288
	ds_read_b32 v237, v246 offset:14336
	ds_read_b32 v238, v246 offset:16384
	ds_read_b32 v239, v246 offset:18432
	ds_read_b32 v240, v246 offset:20480
	ds_read_b32 v241, v246 offset:22528
	ds_read_b32 v242, v246 offset:24576
	ds_read_b32 v243, v246 offset:26624
	ds_read_b32 v244, v246 offset:28672
	ds_read_b32 v245, v246 offset:30720
	ds_read_b32 v246, v246 offset:32768
	s_waitcnt lgkmcnt(0)
	s_nop 0
	s_nop 0
	s_add_i32 s6, s4, -3
	s_branch .LBB0_314
